# XN from norm0/norm2 stored K-blocked in the GU tile LDS-image order (contiguous 8 KB per K-step for the A operand of GU1/GU2)
# speedup vs baseline: 1.0233x; 1.0233x over previous
.LBB0_5:
	s_waitcnt lgkmcnt(0)
	v_add_f32_e32 v46, v46, v47
	v_fmamk_f32 v46, v46, 0x3a800000, v217
	v_mul_f32_e32 v47, 0x4b800000, v46
	v_cmp_gt_f32_e32 vcc, s75, v46
	v_mov_b32_e32 v64, v22
	v_mov_b32_e32 v65, v24
	v_cndmask_b32_e32 v46, v46, v47, vcc
	v_rsq_f32_e32 v46, v46
	v_mov_b32_e32 v24, v23
	v_readlane_b32 s96, v253, 4
	v_readlane_b32 s97, v253, 5
	v_and_b32_e32 v63, 63, v216
	v_lshrrev_b32_e32 v62, 3, v63
	v_lshlrev_b32_e32 v62, 13, v62
	v_and_b32_e32 v63, 7, v63
	v_lshl_or_b32 v62, v63, 3, v62
	v_and_b32_e32 v63, 8, v30
	v_mul_u32_u24_e32 v63, 6, v63
	v_xor_b32_e32 v62, v62, v63
	v_and_b32_e32 v63, 0x7f, v30
	v_lshl_add_u32 v62, v63, 6, v62
	v_lshrrev_b32_e32 v63, 7, v30
	v_lshl_add_u32 v62, v63, 18, v62
	v_mul_f32_e32 v47, 0x45800000, v46
	v_cndmask_b32_e32 v46, v46, v47, vcc
	v_pk_mul_f32 v[48:49], v[0:1], v[46:47] op_sel_hi:[1,0]
	v_pk_mul_f32 v[50:51], v[38:39], v[46:47] op_sel_hi:[1,0]
	v_pk_mul_f32 v[48:49], v[64:65], v[48:49]
	v_pk_mul_f32 v[22:23], v[24:25], v[50:51]
	v_and_b32_sdwa v25, v48, v232 dst_sel:DWORD dst_unused:UNUSED_PAD src0_sel:WORD_1 src1_sel:DWORD
	v_add3_u32 v25, v48, v25, s69
	v_and_b32_sdwa v31, v23, v232 dst_sel:DWORD dst_unused:UNUSED_PAD src0_sel:WORD_1 src1_sel:DWORD
	v_and_b32_sdwa v48, v22, v232 dst_sel:DWORD dst_unused:UNUSED_PAD src0_sel:WORD_1 src1_sel:DWORD
	v_and_b32_sdwa v24, v49, v232 dst_sel:DWORD dst_unused:UNUSED_PAD src0_sel:WORD_1 src1_sel:DWORD
	v_add3_u32 v23, v23, v31, s69
	v_add3_u32 v22, v22, v48, s69
	v_add3_u32 v24, v49, v24, s69
	v_and_b32_e32 v23, 0xffff0000, v23
	v_and_b32_e32 v22, 0xffff0000, v22
	v_or_b32_sdwa v23, v23, v24 dst_sel:DWORD dst_unused:UNUSED_PAD src0_sel:DWORD src1_sel:WORD_1
	v_or_b32_sdwa v22, v22, v25 dst_sel:DWORD dst_unused:UNUSED_PAD src0_sel:DWORD src1_sel:WORD_1
	v_pk_mul_f32 v[52:53], v[4:5], v[46:47] op_sel_hi:[1,0]
	global_store_dwordx2 v62, v[22:23], s[96:97]
	v_mov_b32_e32 v22, v14
	v_mov_b32_e32 v23, v16
	v_pk_mul_f32 v[54:55], v[2:3], v[46:47] op_sel_hi:[1,0]
	v_pk_mul_f32 v[22:23], v[22:23], v[52:53]
	v_mov_b32_e32 v16, v15
	v_pk_mul_f32 v[14:15], v[16:17], v[54:55]
	v_and_b32_sdwa v16, v23, v232 dst_sel:DWORD dst_unused:UNUSED_PAD src0_sel:WORD_1 src1_sel:DWORD
	v_and_b32_sdwa v17, v22, v232 dst_sel:DWORD dst_unused:UNUSED_PAD src0_sel:WORD_1 src1_sel:DWORD
	v_add3_u32 v17, v22, v17, s69
	v_add3_u32 v16, v23, v16, s69
	v_and_b32_sdwa v22, v15, v232 dst_sel:DWORD dst_unused:UNUSED_PAD src0_sel:WORD_1 src1_sel:DWORD
	v_and_b32_sdwa v23, v14, v232 dst_sel:DWORD dst_unused:UNUSED_PAD src0_sel:WORD_1 src1_sel:DWORD
	v_add3_u32 v15, v15, v22, s69
	v_add3_u32 v14, v14, v23, s69
	v_and_b32_e32 v15, 0xffff0000, v15
	v_and_b32_e32 v14, 0xffff0000, v14
	v_or_b32_sdwa v15, v15, v16 dst_sel:DWORD dst_unused:UNUSED_PAD src0_sel:DWORD src1_sel:WORD_1
	v_or_b32_sdwa v14, v14, v17 dst_sel:DWORD dst_unused:UNUSED_PAD src0_sel:DWORD src1_sel:WORD_1
	v_pk_mul_f32 v[56:57], v[8:9], v[46:47] op_sel_hi:[1,0]
	v_add_u32_e32 v62, 0x10000, v62
	global_store_dwordx2 v62, v[14:15], s[96:97]
	v_mov_b32_e32 v14, v26
	v_mov_b32_e32 v15, v28
	v_pk_mul_f32 v[58:59], v[6:7], v[46:47] op_sel_hi:[1,0]
	v_pk_mul_f32 v[14:15], v[14:15], v[56:57]
	v_mov_b32_e32 v28, v27
	v_pk_mul_f32 v[16:17], v[28:29], v[58:59]
	v_and_b32_sdwa v22, v15, v232 dst_sel:DWORD dst_unused:UNUSED_PAD src0_sel:WORD_1 src1_sel:DWORD
	v_and_b32_sdwa v23, v14, v232 dst_sel:DWORD dst_unused:UNUSED_PAD src0_sel:WORD_1 src1_sel:DWORD
	v_add3_u32 v14, v14, v23, s69
	v_add3_u32 v15, v15, v22, s69
	v_and_b32_sdwa v22, v17, v232 dst_sel:DWORD dst_unused:UNUSED_PAD src0_sel:WORD_1 src1_sel:DWORD
	v_and_b32_sdwa v23, v16, v232 dst_sel:DWORD dst_unused:UNUSED_PAD src0_sel:WORD_1 src1_sel:DWORD
	v_add3_u32 v17, v17, v22, s69
	v_add3_u32 v16, v16, v23, s69
	v_and_b32_e32 v17, 0xffff0000, v17
	v_and_b32_e32 v16, 0xffff0000, v16
	v_or_b32_sdwa v15, v17, v15 dst_sel:DWORD dst_unused:UNUSED_PAD src0_sel:DWORD src1_sel:WORD_1
	v_or_b32_sdwa v14, v16, v14 dst_sel:DWORD dst_unused:UNUSED_PAD src0_sel:DWORD src1_sel:WORD_1
	v_pk_mul_f32 v[60:61], v[12:13], v[46:47] op_sel_hi:[1,0]
	v_add_u32_e32 v62, 0x10000, v62
	global_store_dwordx2 v62, v[14:15], s[96:97]
	v_mov_b32_e32 v14, v18
	v_mov_b32_e32 v15, v20
	v_pk_mul_f32 v[46:47], v[10:11], v[46:47] op_sel_hi:[1,0]
	v_pk_mul_f32 v[14:15], v[14:15], v[60:61]
	v_mov_b32_e32 v20, v19
	v_pk_mul_f32 v[16:17], v[20:21], v[46:47]
	v_and_b32_sdwa v18, v15, v232 dst_sel:DWORD dst_unused:UNUSED_PAD src0_sel:WORD_1 src1_sel:DWORD
	v_and_b32_sdwa v19, v14, v232 dst_sel:DWORD dst_unused:UNUSED_PAD src0_sel:WORD_1 src1_sel:DWORD
	v_add3_u32 v14, v14, v19, s69
	v_add3_u32 v15, v15, v18, s69
	v_and_b32_sdwa v18, v17, v232 dst_sel:DWORD dst_unused:UNUSED_PAD src0_sel:WORD_1 src1_sel:DWORD
	v_and_b32_sdwa v19, v16, v232 dst_sel:DWORD dst_unused:UNUSED_PAD src0_sel:WORD_1 src1_sel:DWORD
	v_add3_u32 v17, v17, v18, s69
	v_add3_u32 v16, v16, v19, s69
	v_add_u32_e32 v30, s81, v30
	v_and_b32_e32 v17, 0xffff0000, v17
	v_and_b32_e32 v16, 0xffff0000, v16
	v_cmp_lt_i32_e32 vcc, s76, v30
	v_or_b32_sdwa v15, v17, v15 dst_sel:DWORD dst_unused:UNUSED_PAD src0_sel:DWORD src1_sel:WORD_1
	v_or_b32_sdwa v14, v16, v14 dst_sel:DWORD dst_unused:UNUSED_PAD src0_sel:DWORD src1_sel:WORD_1
	s_or_b64 s[12:13], vcc, s[12:13]
	v_add_u32_e32 v62, 0x10000, v62
	global_store_dwordx2 v62, v[14:15], s[96:97]
	s_andn2_b64 exec, exec, s[12:13]
	s_cbranch_execz .LBB0_22

.LBB0_96:
	s_andn2_b64 vcc, exec, s[2:3]
	s_cbranch_vccnz .LBB0_90
	v_readlane_b32 s2, v253, 4
	v_readlane_b32 s3, v253, 5
	s_lshl_b32 s13, s54, 18
	s_add_u32 s2, s2, s13
	s_addc_u32 s3, s3, 0
	s_lshl_b32 s13, s56, 19
	s_add_u32 s4, s50, 0x4490000
	s_addc_u32 s5, s51, 0
	s_add_u32 s4, s4, s13
	s_addc_u32 s5, s5, 0
	v_and_b32_e32 v152, 63, v216
	v_lshrrev_b32_e32 v153, 6, v216
	v_lshrrev_b32_e32 v154, 2, v152
	v_and_b32_e32 v155, 3, v152
	v_readfirstlane_b32 s11, v153
	v_lshrrev_b32_e32 v156, 3, v154
	v_mul_u32_u24_e32 v156, 3, v156
	v_xor_b32_e32 v156, v155, v156
	v_lshlrev_b32_e32 v156, 4, v156
	v_lshl_add_u32 v157, v153, 5, v154
	v_lshlrev_b32_e32 v163, 4, v152
	v_lshl_add_u32 v203, v153, 11, v163
	v_add_u32_e32 v204, 0x400, v203
	v_lshl_add_u32 v157, v153, 6, v154
	v_lshlrev_b32_e32 v163, 4, v152
	v_lshl_add_u32 v205, v153, 12, v163
	v_add_u32_e32 v206, 0x400, v205
	v_add_u32_e32 v207, 0x800, v205
	v_add_u32_e32 v208, 0xc00, v205
	v_and_b32_e32 v158, 15, v152
	v_lshrrev_b32_e32 v159, 4, v152
	v_lshrrev_b32_e32 v160, 3, v158
	v_mul_u32_u24_e32 v160, 3, v160
	v_xor_b32_e32 v160, v159, v160
	v_lshlrev_b32_e32 v160, 4, v160
	v_lshl_add_u32 v160, v158, 6, v160
	v_lshrrev_b32_e32 v161, 1, v153
	v_and_b32_e32 v162, 1, v153
	v_lshl_add_u32 v209, v161, 12, v160
	v_lshl_add_u32 v210, v162, 13, v160
	s_lshl_b32 s12, s11, 12
	s_lshl_b32 s11, s11, 11
	s_barrier
	s_add_u32 m0, s11, 0x0
	s_nop 0
	global_load_lds_dwordx4 v203, s[2:3]
	s_add_u32 m0, s11, 0x400
	s_nop 0
	global_load_lds_dwordx4 v204, s[2:3]
	s_add_u32 m0, s12, 0x2000
	s_nop 0
	global_load_lds_dwordx4 v205, s[4:5]
	s_add_u32 m0, s12, 0x2400
	s_nop 0
	global_load_lds_dwordx4 v206, s[4:5]
	s_add_u32 m0, s12, 0x2800
	s_nop 0
	global_load_lds_dwordx4 v207, s[4:5]
	s_add_u32 m0, s12, 0x2c00
	s_nop 0
	global_load_lds_dwordx4 v208, s[4:5]
	s_add_u32 s2, s2, 0x2000
	s_addc_u32 s3, s3, 0
	s_add_u32 s4, s4, 0x4000
	s_addc_u32 s5, s5, 0
	s_add_u32 m0, s11, 0x6000
	s_nop 0
	global_load_lds_dwordx4 v203, s[2:3]
	s_add_u32 m0, s11, 0x6400
	s_nop 0
	global_load_lds_dwordx4 v204, s[2:3]
	s_add_u32 m0, s12, 0x8000
	s_nop 0
	global_load_lds_dwordx4 v205, s[4:5]
	s_add_u32 m0, s12, 0x8400
	s_nop 0
	global_load_lds_dwordx4 v206, s[4:5]
	s_add_u32 m0, s12, 0x8800
	s_nop 0
	global_load_lds_dwordx4 v207, s[4:5]
	s_add_u32 m0, s12, 0x8c00
	s_nop 0
	global_load_lds_dwordx4 v208, s[4:5]
	s_add_u32 s2, s2, 0x2000
	s_addc_u32 s3, s3, 0
	s_add_u32 s4, s4, 0x4000
	s_addc_u32 s5, s5, 0
	v_mov_b32_e32 v172, 0
	v_mov_b32_e32 v173, 0
	v_mov_b32_e32 v174, 0
	v_mov_b32_e32 v175, 0
	v_mov_b32_e32 v168, 0
	v_mov_b32_e32 v169, 0
	v_mov_b32_e32 v170, 0
	v_mov_b32_e32 v171, 0
	v_mov_b32_e32 v116, 0
	v_mov_b32_e32 v117, 0
	v_mov_b32_e32 v118, 0
	v_mov_b32_e32 v119, 0
	v_mov_b32_e32 v112, 0
	v_mov_b32_e32 v113, 0
	v_mov_b32_e32 v114, 0
	v_mov_b32_e32 v115, 0
	v_mov_b32_e32 v108, 0
	v_mov_b32_e32 v109, 0
	v_mov_b32_e32 v110, 0
	v_mov_b32_e32 v111, 0
	v_mov_b32_e32 v104, 0
	v_mov_b32_e32 v105, 0
	v_mov_b32_e32 v106, 0
	v_mov_b32_e32 v107, 0
	v_mov_b32_e32 v100, 0
	v_mov_b32_e32 v101, 0
	v_mov_b32_e32 v102, 0
	v_mov_b32_e32 v103, 0
	v_mov_b32_e32 v96, 0
	v_mov_b32_e32 v97, 0
	v_mov_b32_e32 v98, 0
	v_mov_b32_e32 v99, 0
	v_mov_b32_e32 v92, 0
	v_mov_b32_e32 v93, 0
	v_mov_b32_e32 v94, 0
	v_mov_b32_e32 v95, 0
	v_mov_b32_e32 v88, 0
	v_mov_b32_e32 v89, 0
	v_mov_b32_e32 v90, 0
	v_mov_b32_e32 v91, 0
	v_mov_b32_e32 v84, 0
	v_mov_b32_e32 v85, 0
	v_mov_b32_e32 v86, 0
	v_mov_b32_e32 v87, 0
	v_mov_b32_e32 v80, 0
	v_mov_b32_e32 v81, 0
	v_mov_b32_e32 v82, 0
	v_mov_b32_e32 v83, 0
	v_mov_b32_e32 v76, 0
	v_mov_b32_e32 v77, 0
	v_mov_b32_e32 v78, 0
	v_mov_b32_e32 v79, 0
	v_mov_b32_e32 v72, 0
	v_mov_b32_e32 v73, 0
	v_mov_b32_e32 v74, 0
	v_mov_b32_e32 v75, 0
	v_mov_b32_e32 v68, 0
	v_mov_b32_e32 v69, 0
	v_mov_b32_e32 v70, 0
	v_mov_b32_e32 v71, 0
	v_mov_b32_e32 v64, 0
	v_mov_b32_e32 v65, 0
	v_mov_b32_e32 v66, 0
	v_mov_b32_e32 v67, 0
	v_mov_b32_e32 v60, 0
	v_mov_b32_e32 v61, 0
	v_mov_b32_e32 v62, 0
	v_mov_b32_e32 v63, 0
	v_mov_b32_e32 v56, 0
	v_mov_b32_e32 v57, 0
	v_mov_b32_e32 v58, 0
	v_mov_b32_e32 v59, 0
	v_mov_b32_e32 v52, 0
	v_mov_b32_e32 v53, 0
	v_mov_b32_e32 v54, 0
	v_mov_b32_e32 v55, 0
	v_mov_b32_e32 v48, 0
	v_mov_b32_e32 v49, 0
	v_mov_b32_e32 v50, 0
	v_mov_b32_e32 v51, 0
	v_mov_b32_e32 v44, 0
	v_mov_b32_e32 v45, 0
	v_mov_b32_e32 v46, 0
	v_mov_b32_e32 v47, 0
	v_mov_b32_e32 v40, 0
	v_mov_b32_e32 v41, 0
	v_mov_b32_e32 v42, 0
	v_mov_b32_e32 v43, 0
	v_mov_b32_e32 v36, 0
	v_mov_b32_e32 v37, 0
	v_mov_b32_e32 v38, 0
	v_mov_b32_e32 v39, 0
	v_mov_b32_e32 v32, 0
	v_mov_b32_e32 v33, 0
	v_mov_b32_e32 v34, 0
	v_mov_b32_e32 v35, 0
	v_mov_b32_e32 v28, 0
	v_mov_b32_e32 v29, 0
	v_mov_b32_e32 v30, 0
	v_mov_b32_e32 v31, 0
	v_mov_b32_e32 v24, 0
	v_mov_b32_e32 v25, 0
	v_mov_b32_e32 v26, 0
	v_mov_b32_e32 v27, 0
	v_mov_b32_e32 v20, 0
	v_mov_b32_e32 v21, 0
	v_mov_b32_e32 v22, 0
	v_mov_b32_e32 v23, 0
	v_mov_b32_e32 v16, 0
	v_mov_b32_e32 v17, 0
	v_mov_b32_e32 v18, 0
	v_mov_b32_e32 v19, 0
	v_mov_b32_e32 v12, 0
	v_mov_b32_e32 v13, 0
	v_mov_b32_e32 v14, 0
	v_mov_b32_e32 v15, 0
	v_mov_b32_e32 v8, 0
	v_mov_b32_e32 v9, 0
	v_mov_b32_e32 v10, 0
	v_mov_b32_e32 v11, 0
	v_mov_b32_e32 v4, 0
	v_mov_b32_e32 v5, 0
	v_mov_b32_e32 v6, 0
	v_mov_b32_e32 v7, 0
	v_mov_b32_e32 v0, 0
	v_mov_b32_e32 v1, 0
	v_mov_b32_e32 v2, 0
	v_mov_b32_e32 v3, 0
	s_waitcnt vmcnt(6)
	s_barrier
	ds_read_b128 v[120:123], v209 offset:0
	ds_read_b128 v[124:127], v209 offset:1024
	ds_read_b128 v[128:131], v209 offset:2048
	ds_read_b128 v[132:135], v209 offset:3072
	ds_read_b128 v[152:155], v210 offset:8192
	ds_read_b128 v[156:159], v210 offset:9216
	ds_read_b128 v[160:163], v210 offset:10240
	ds_read_b128 v[164:167], v210 offset:11264
	ds_read_b128 v[176:179], v210 offset:12288
	ds_read_b128 v[180:183], v210 offset:13312
	s_add_u32 m0, s11, 0xc000
	s_nop 0
	global_load_lds_dwordx4 v203, s[2:3]
	s_add_u32 m0, s11, 0xc400
	s_nop 0
	global_load_lds_dwordx4 v204, s[2:3]
	s_add_u32 m0, s12, 0xe000
	s_nop 0
	global_load_lds_dwordx4 v205, s[4:5]
	s_add_u32 m0, s12, 0xe400
	s_nop 0
	global_load_lds_dwordx4 v206, s[4:5]
	s_add_u32 m0, s12, 0xe800
	s_nop 0
	global_load_lds_dwordx4 v207, s[4:5]
	s_add_u32 m0, s12, 0xec00
	s_nop 0
	global_load_lds_dwordx4 v208, s[4:5]
	s_add_u32 s2, s2, 0x2000
	s_addc_u32 s3, s3, 0
	s_add_u32 s4, s4, 0x4000
	s_addc_u32 s5, s5, 0
	ds_read_b128 v[184:187], v210 offset:14336
	ds_read_b128 v[188:191], v210 offset:15360
	s_waitcnt lgkmcnt(7)
	v_mfma_f32_16x16x32_bf16 v[172:175], v[152:155], v[120:123], v[172:175]
	v_mfma_f32_16x16x32_bf16 v[92:95], v[152:155], v[124:127], v[92:95]
	v_mfma_f32_16x16x32_bf16 v[60:63], v[152:155], v[128:131], v[60:63]
	v_mfma_f32_16x16x32_bf16 v[28:31], v[152:155], v[132:135], v[28:31]
	s_waitcnt lgkmcnt(6)
	v_mfma_f32_16x16x32_bf16 v[168:171], v[156:159], v[120:123], v[168:171]
	v_mfma_f32_16x16x32_bf16 v[88:91], v[156:159], v[124:127], v[88:91]
	v_mfma_f32_16x16x32_bf16 v[56:59], v[156:159], v[128:131], v[56:59]
	v_mfma_f32_16x16x32_bf16 v[24:27], v[156:159], v[132:135], v[24:27]
	s_waitcnt lgkmcnt(5)
	v_mfma_f32_16x16x32_bf16 v[116:119], v[160:163], v[120:123], v[116:119]
	v_mfma_f32_16x16x32_bf16 v[84:87], v[160:163], v[124:127], v[84:87]
	v_mfma_f32_16x16x32_bf16 v[52:55], v[160:163], v[128:131], v[52:55]
	v_mfma_f32_16x16x32_bf16 v[20:23], v[160:163], v[132:135], v[20:23]
	s_waitcnt lgkmcnt(4)
	v_mfma_f32_16x16x32_bf16 v[112:115], v[164:167], v[120:123], v[112:115]
	v_mfma_f32_16x16x32_bf16 v[80:83], v[164:167], v[124:127], v[80:83]
	v_mfma_f32_16x16x32_bf16 v[48:51], v[164:167], v[128:131], v[48:51]
	v_mfma_f32_16x16x32_bf16 v[16:19], v[164:167], v[132:135], v[16:19]
	s_waitcnt lgkmcnt(3)
	v_mfma_f32_16x16x32_bf16 v[108:111], v[176:179], v[120:123], v[108:111]
	v_mfma_f32_16x16x32_bf16 v[76:79], v[176:179], v[124:127], v[76:79]
	v_mfma_f32_16x16x32_bf16 v[44:47], v[176:179], v[128:131], v[44:47]
	v_mfma_f32_16x16x32_bf16 v[12:15], v[176:179], v[132:135], v[12:15]
	s_waitcnt lgkmcnt(2)
	v_mfma_f32_16x16x32_bf16 v[104:107], v[180:183], v[120:123], v[104:107]
	v_mfma_f32_16x16x32_bf16 v[72:75], v[180:183], v[124:127], v[72:75]
	v_mfma_f32_16x16x32_bf16 v[40:43], v[180:183], v[128:131], v[40:43]
	v_mfma_f32_16x16x32_bf16 v[8:11], v[180:183], v[132:135], v[8:11]
	s_waitcnt lgkmcnt(0)
	s_mov_b32 s13, 5
.Lg1_loop:
	s_waitcnt vmcnt(6)
	s_barrier
	ds_read_b128 v[136:139], v209 offset:24576
	ds_read_b128 v[140:143], v209 offset:25600
	ds_read_b128 v[144:147], v209 offset:26624
	ds_read_b128 v[148:151], v209 offset:27648
	ds_read_b128 v[152:155], v210 offset:32768
	ds_read_b128 v[156:159], v210 offset:33792
	ds_read_b128 v[160:163], v210 offset:34816
	ds_read_b128 v[164:167], v210 offset:35840
	ds_read_b128 v[176:179], v210 offset:36864
	ds_read_b128 v[180:183], v210 offset:37888
	v_mfma_f32_16x16x32_bf16 v[100:103], v[184:187], v[120:123], v[100:103]
	s_add_u32 m0, s11, 0x0
	v_mfma_f32_16x16x32_bf16 v[68:71], v[184:187], v[124:127], v[68:71]
	global_load_lds_dwordx4 v203, s[2:3]
	s_add_u32 m0, s11, 0x400
	v_mfma_f32_16x16x32_bf16 v[36:39], v[184:187], v[128:131], v[36:39]
	global_load_lds_dwordx4 v204, s[2:3]
	s_add_u32 m0, s12, 0x2000
	v_mfma_f32_16x16x32_bf16 v[4:7], v[184:187], v[132:135], v[4:7]
	global_load_lds_dwordx4 v205, s[4:5]
	s_add_u32 m0, s12, 0x2400
	v_mfma_f32_16x16x32_bf16 v[96:99], v[188:191], v[120:123], v[96:99]
	global_load_lds_dwordx4 v206, s[4:5]
	s_add_u32 m0, s12, 0x2800
	v_mfma_f32_16x16x32_bf16 v[64:67], v[188:191], v[124:127], v[64:67]
	global_load_lds_dwordx4 v207, s[4:5]
	s_add_u32 m0, s12, 0x2c00
	v_mfma_f32_16x16x32_bf16 v[32:35], v[188:191], v[128:131], v[32:35]
	global_load_lds_dwordx4 v208, s[4:5]
	v_mfma_f32_16x16x32_bf16 v[0:3], v[188:191], v[132:135], v[0:3]
	s_add_u32 s2, s2, 0x2000
	s_addc_u32 s3, s3, 0
	s_add_u32 s4, s4, 0x4000
	s_addc_u32 s5, s5, 0
	ds_read_b128 v[184:187], v210 offset:38912
	ds_read_b128 v[188:191], v210 offset:39936
	s_waitcnt lgkmcnt(7)
	v_mfma_f32_16x16x32_bf16 v[172:175], v[152:155], v[136:139], v[172:175]
	v_mfma_f32_16x16x32_bf16 v[92:95], v[152:155], v[140:143], v[92:95]
	v_mfma_f32_16x16x32_bf16 v[60:63], v[152:155], v[144:147], v[60:63]
	v_mfma_f32_16x16x32_bf16 v[28:31], v[152:155], v[148:151], v[28:31]
	s_waitcnt lgkmcnt(6)
	v_mfma_f32_16x16x32_bf16 v[168:171], v[156:159], v[136:139], v[168:171]
	v_mfma_f32_16x16x32_bf16 v[88:91], v[156:159], v[140:143], v[88:91]
	v_mfma_f32_16x16x32_bf16 v[56:59], v[156:159], v[144:147], v[56:59]
	v_mfma_f32_16x16x32_bf16 v[24:27], v[156:159], v[148:151], v[24:27]
	s_waitcnt lgkmcnt(5)
	v_mfma_f32_16x16x32_bf16 v[116:119], v[160:163], v[136:139], v[116:119]
	v_mfma_f32_16x16x32_bf16 v[84:87], v[160:163], v[140:143], v[84:87]
	v_mfma_f32_16x16x32_bf16 v[52:55], v[160:163], v[144:147], v[52:55]
	v_mfma_f32_16x16x32_bf16 v[20:23], v[160:163], v[148:151], v[20:23]
	s_waitcnt lgkmcnt(4)
	v_mfma_f32_16x16x32_bf16 v[112:115], v[164:167], v[136:139], v[112:115]
	v_mfma_f32_16x16x32_bf16 v[80:83], v[164:167], v[140:143], v[80:83]
	v_mfma_f32_16x16x32_bf16 v[48:51], v[164:167], v[144:147], v[48:51]
	v_mfma_f32_16x16x32_bf16 v[16:19], v[164:167], v[148:151], v[16:19]
	s_waitcnt lgkmcnt(3)
	v_mfma_f32_16x16x32_bf16 v[108:111], v[176:179], v[136:139], v[108:111]
	v_mfma_f32_16x16x32_bf16 v[76:79], v[176:179], v[140:143], v[76:79]
	v_mfma_f32_16x16x32_bf16 v[44:47], v[176:179], v[144:147], v[44:47]
	v_mfma_f32_16x16x32_bf16 v[12:15], v[176:179], v[148:151], v[12:15]
	s_waitcnt lgkmcnt(2)
	v_mfma_f32_16x16x32_bf16 v[104:107], v[180:183], v[136:139], v[104:107]
	v_mfma_f32_16x16x32_bf16 v[72:75], v[180:183], v[140:143], v[72:75]
	v_mfma_f32_16x16x32_bf16 v[40:43], v[180:183], v[144:147], v[40:43]
	v_mfma_f32_16x16x32_bf16 v[8:11], v[180:183], v[148:151], v[8:11]
	s_waitcnt lgkmcnt(0)
	s_waitcnt vmcnt(6)
	s_barrier
	ds_read_b128 v[120:123], v209 offset:49152
	ds_read_b128 v[124:127], v209 offset:50176
	ds_read_b128 v[128:131], v209 offset:51200
	ds_read_b128 v[132:135], v209 offset:52224
	ds_read_b128 v[152:155], v210 offset:57344
	ds_read_b128 v[156:159], v210 offset:58368
	ds_read_b128 v[160:163], v210 offset:59392
	ds_read_b128 v[164:167], v210 offset:60416
	ds_read_b128 v[176:179], v210 offset:61440
	ds_read_b128 v[180:183], v210 offset:62464
	v_mfma_f32_16x16x32_bf16 v[100:103], v[184:187], v[136:139], v[100:103]
	s_add_u32 m0, s11, 0x6000
	v_mfma_f32_16x16x32_bf16 v[68:71], v[184:187], v[140:143], v[68:71]
	global_load_lds_dwordx4 v203, s[2:3]
	s_add_u32 m0, s11, 0x6400
	v_mfma_f32_16x16x32_bf16 v[36:39], v[184:187], v[144:147], v[36:39]
	global_load_lds_dwordx4 v204, s[2:3]
	s_add_u32 m0, s12, 0x8000
	v_mfma_f32_16x16x32_bf16 v[4:7], v[184:187], v[148:151], v[4:7]
	global_load_lds_dwordx4 v205, s[4:5]
	s_add_u32 m0, s12, 0x8400
	v_mfma_f32_16x16x32_bf16 v[96:99], v[188:191], v[136:139], v[96:99]
	global_load_lds_dwordx4 v206, s[4:5]
	s_add_u32 m0, s12, 0x8800
	v_mfma_f32_16x16x32_bf16 v[64:67], v[188:191], v[140:143], v[64:67]
	global_load_lds_dwordx4 v207, s[4:5]
	s_add_u32 m0, s12, 0x8c00
	v_mfma_f32_16x16x32_bf16 v[32:35], v[188:191], v[144:147], v[32:35]
	global_load_lds_dwordx4 v208, s[4:5]
	v_mfma_f32_16x16x32_bf16 v[0:3], v[188:191], v[148:151], v[0:3]
	s_add_u32 s2, s2, 0x2000
	s_addc_u32 s3, s3, 0
	s_add_u32 s4, s4, 0x4000
	s_addc_u32 s5, s5, 0
	ds_read_b128 v[184:187], v210 offset:63488
	ds_read_b128 v[188:191], v210 offset:64512
	s_waitcnt lgkmcnt(7)
	v_mfma_f32_16x16x32_bf16 v[172:175], v[152:155], v[120:123], v[172:175]
	v_mfma_f32_16x16x32_bf16 v[92:95], v[152:155], v[124:127], v[92:95]
	v_mfma_f32_16x16x32_bf16 v[60:63], v[152:155], v[128:131], v[60:63]
	v_mfma_f32_16x16x32_bf16 v[28:31], v[152:155], v[132:135], v[28:31]
	s_waitcnt lgkmcnt(6)
	v_mfma_f32_16x16x32_bf16 v[168:171], v[156:159], v[120:123], v[168:171]
	v_mfma_f32_16x16x32_bf16 v[88:91], v[156:159], v[124:127], v[88:91]
	v_mfma_f32_16x16x32_bf16 v[56:59], v[156:159], v[128:131], v[56:59]
	v_mfma_f32_16x16x32_bf16 v[24:27], v[156:159], v[132:135], v[24:27]
	s_waitcnt lgkmcnt(5)
	v_mfma_f32_16x16x32_bf16 v[116:119], v[160:163], v[120:123], v[116:119]
	v_mfma_f32_16x16x32_bf16 v[84:87], v[160:163], v[124:127], v[84:87]
	v_mfma_f32_16x16x32_bf16 v[52:55], v[160:163], v[128:131], v[52:55]
	v_mfma_f32_16x16x32_bf16 v[20:23], v[160:163], v[132:135], v[20:23]
	s_waitcnt lgkmcnt(4)
	v_mfma_f32_16x16x32_bf16 v[112:115], v[164:167], v[120:123], v[112:115]
	v_mfma_f32_16x16x32_bf16 v[80:83], v[164:167], v[124:127], v[80:83]
	v_mfma_f32_16x16x32_bf16 v[48:51], v[164:167], v[128:131], v[48:51]
	v_mfma_f32_16x16x32_bf16 v[16:19], v[164:167], v[132:135], v[16:19]
	s_waitcnt lgkmcnt(3)
	v_mfma_f32_16x16x32_bf16 v[108:111], v[176:179], v[120:123], v[108:111]
	v_mfma_f32_16x16x32_bf16 v[76:79], v[176:179], v[124:127], v[76:79]
	v_mfma_f32_16x16x32_bf16 v[44:47], v[176:179], v[128:131], v[44:47]
	v_mfma_f32_16x16x32_bf16 v[12:15], v[176:179], v[132:135], v[12:15]
	s_waitcnt lgkmcnt(2)
	v_mfma_f32_16x16x32_bf16 v[104:107], v[180:183], v[120:123], v[104:107]
	v_mfma_f32_16x16x32_bf16 v[72:75], v[180:183], v[124:127], v[72:75]
	v_mfma_f32_16x16x32_bf16 v[40:43], v[180:183], v[128:131], v[40:43]
	v_mfma_f32_16x16x32_bf16 v[8:11], v[180:183], v[132:135], v[8:11]
	s_waitcnt lgkmcnt(0)
	s_waitcnt vmcnt(6)
	s_barrier
	ds_read_b128 v[136:139], v209 offset:0
	ds_read_b128 v[140:143], v209 offset:1024
	ds_read_b128 v[144:147], v209 offset:2048
	ds_read_b128 v[148:151], v209 offset:3072
	ds_read_b128 v[152:155], v210 offset:8192
	ds_read_b128 v[156:159], v210 offset:9216
	ds_read_b128 v[160:163], v210 offset:10240
	ds_read_b128 v[164:167], v210 offset:11264
	ds_read_b128 v[176:179], v210 offset:12288
	ds_read_b128 v[180:183], v210 offset:13312
	v_mfma_f32_16x16x32_bf16 v[100:103], v[184:187], v[120:123], v[100:103]
	s_add_u32 m0, s11, 0xc000
	v_mfma_f32_16x16x32_bf16 v[68:71], v[184:187], v[124:127], v[68:71]
	global_load_lds_dwordx4 v203, s[2:3]
	s_add_u32 m0, s11, 0xc400
	v_mfma_f32_16x16x32_bf16 v[36:39], v[184:187], v[128:131], v[36:39]
	global_load_lds_dwordx4 v204, s[2:3]
	s_add_u32 m0, s12, 0xe000
	v_mfma_f32_16x16x32_bf16 v[4:7], v[184:187], v[132:135], v[4:7]
	global_load_lds_dwordx4 v205, s[4:5]
	s_add_u32 m0, s12, 0xe400
	v_mfma_f32_16x16x32_bf16 v[96:99], v[188:191], v[120:123], v[96:99]
	global_load_lds_dwordx4 v206, s[4:5]
	s_add_u32 m0, s12, 0xe800
	v_mfma_f32_16x16x32_bf16 v[64:67], v[188:191], v[124:127], v[64:67]
	global_load_lds_dwordx4 v207, s[4:5]
	s_add_u32 m0, s12, 0xec00
	v_mfma_f32_16x16x32_bf16 v[32:35], v[188:191], v[128:131], v[32:35]
	global_load_lds_dwordx4 v208, s[4:5]
	v_mfma_f32_16x16x32_bf16 v[0:3], v[188:191], v[132:135], v[0:3]
	s_add_u32 s2, s2, 0x2000
	s_addc_u32 s3, s3, 0
	s_add_u32 s4, s4, 0x4000
	s_addc_u32 s5, s5, 0
	ds_read_b128 v[184:187], v210 offset:14336
	ds_read_b128 v[188:191], v210 offset:15360
	s_waitcnt lgkmcnt(7)
	v_mfma_f32_16x16x32_bf16 v[172:175], v[152:155], v[136:139], v[172:175]
	v_mfma_f32_16x16x32_bf16 v[92:95], v[152:155], v[140:143], v[92:95]
	v_mfma_f32_16x16x32_bf16 v[60:63], v[152:155], v[144:147], v[60:63]
	v_mfma_f32_16x16x32_bf16 v[28:31], v[152:155], v[148:151], v[28:31]
	s_waitcnt lgkmcnt(6)
	v_mfma_f32_16x16x32_bf16 v[168:171], v[156:159], v[136:139], v[168:171]
	v_mfma_f32_16x16x32_bf16 v[88:91], v[156:159], v[140:143], v[88:91]
	v_mfma_f32_16x16x32_bf16 v[56:59], v[156:159], v[144:147], v[56:59]
	v_mfma_f32_16x16x32_bf16 v[24:27], v[156:159], v[148:151], v[24:27]
	s_waitcnt lgkmcnt(5)
	v_mfma_f32_16x16x32_bf16 v[116:119], v[160:163], v[136:139], v[116:119]
	v_mfma_f32_16x16x32_bf16 v[84:87], v[160:163], v[140:143], v[84:87]
	v_mfma_f32_16x16x32_bf16 v[52:55], v[160:163], v[144:147], v[52:55]
	v_mfma_f32_16x16x32_bf16 v[20:23], v[160:163], v[148:151], v[20:23]
	s_waitcnt lgkmcnt(4)
	v_mfma_f32_16x16x32_bf16 v[112:115], v[164:167], v[136:139], v[112:115]
	v_mfma_f32_16x16x32_bf16 v[80:83], v[164:167], v[140:143], v[80:83]
	v_mfma_f32_16x16x32_bf16 v[48:51], v[164:167], v[144:147], v[48:51]
	v_mfma_f32_16x16x32_bf16 v[16:19], v[164:167], v[148:151], v[16:19]
	s_waitcnt lgkmcnt(3)
	v_mfma_f32_16x16x32_bf16 v[108:111], v[176:179], v[136:139], v[108:111]
	v_mfma_f32_16x16x32_bf16 v[76:79], v[176:179], v[140:143], v[76:79]
	v_mfma_f32_16x16x32_bf16 v[44:47], v[176:179], v[144:147], v[44:47]
	v_mfma_f32_16x16x32_bf16 v[12:15], v[176:179], v[148:151], v[12:15]
	s_waitcnt lgkmcnt(2)
	v_mfma_f32_16x16x32_bf16 v[104:107], v[180:183], v[136:139], v[104:107]
	v_mfma_f32_16x16x32_bf16 v[72:75], v[180:183], v[140:143], v[72:75]
	v_mfma_f32_16x16x32_bf16 v[40:43], v[180:183], v[144:147], v[40:43]
	v_mfma_f32_16x16x32_bf16 v[8:11], v[180:183], v[148:151], v[8:11]
	s_waitcnt lgkmcnt(0)
	s_waitcnt vmcnt(6)
	s_barrier
	ds_read_b128 v[120:123], v209 offset:24576
	ds_read_b128 v[124:127], v209 offset:25600
	ds_read_b128 v[128:131], v209 offset:26624
	ds_read_b128 v[132:135], v209 offset:27648
	ds_read_b128 v[152:155], v210 offset:32768
	ds_read_b128 v[156:159], v210 offset:33792
	ds_read_b128 v[160:163], v210 offset:34816
	ds_read_b128 v[164:167], v210 offset:35840
	ds_read_b128 v[176:179], v210 offset:36864
	ds_read_b128 v[180:183], v210 offset:37888
	v_mfma_f32_16x16x32_bf16 v[100:103], v[184:187], v[136:139], v[100:103]
	s_add_u32 m0, s11, 0x0
	v_mfma_f32_16x16x32_bf16 v[68:71], v[184:187], v[140:143], v[68:71]
	global_load_lds_dwordx4 v203, s[2:3]
	s_add_u32 m0, s11, 0x400
	v_mfma_f32_16x16x32_bf16 v[36:39], v[184:187], v[144:147], v[36:39]
	global_load_lds_dwordx4 v204, s[2:3]
	s_add_u32 m0, s12, 0x2000
	v_mfma_f32_16x16x32_bf16 v[4:7], v[184:187], v[148:151], v[4:7]
	global_load_lds_dwordx4 v205, s[4:5]
	s_add_u32 m0, s12, 0x2400
	v_mfma_f32_16x16x32_bf16 v[96:99], v[188:191], v[136:139], v[96:99]
	global_load_lds_dwordx4 v206, s[4:5]
	s_add_u32 m0, s12, 0x2800
	v_mfma_f32_16x16x32_bf16 v[64:67], v[188:191], v[140:143], v[64:67]
	global_load_lds_dwordx4 v207, s[4:5]
	s_add_u32 m0, s12, 0x2c00
	v_mfma_f32_16x16x32_bf16 v[32:35], v[188:191], v[144:147], v[32:35]
	global_load_lds_dwordx4 v208, s[4:5]
	v_mfma_f32_16x16x32_bf16 v[0:3], v[188:191], v[148:151], v[0:3]
	s_add_u32 s2, s2, 0x2000
	s_addc_u32 s3, s3, 0
	s_add_u32 s4, s4, 0x4000
	s_addc_u32 s5, s5, 0
	ds_read_b128 v[184:187], v210 offset:38912
	ds_read_b128 v[188:191], v210 offset:39936
	s_waitcnt lgkmcnt(7)
	v_mfma_f32_16x16x32_bf16 v[172:175], v[152:155], v[120:123], v[172:175]
	v_mfma_f32_16x16x32_bf16 v[92:95], v[152:155], v[124:127], v[92:95]
	v_mfma_f32_16x16x32_bf16 v[60:63], v[152:155], v[128:131], v[60:63]
	v_mfma_f32_16x16x32_bf16 v[28:31], v[152:155], v[132:135], v[28:31]
	s_waitcnt lgkmcnt(6)
	v_mfma_f32_16x16x32_bf16 v[168:171], v[156:159], v[120:123], v[168:171]
	v_mfma_f32_16x16x32_bf16 v[88:91], v[156:159], v[124:127], v[88:91]
	v_mfma_f32_16x16x32_bf16 v[56:59], v[156:159], v[128:131], v[56:59]
	v_mfma_f32_16x16x32_bf16 v[24:27], v[156:159], v[132:135], v[24:27]
	s_waitcnt lgkmcnt(5)
	v_mfma_f32_16x16x32_bf16 v[116:119], v[160:163], v[120:123], v[116:119]
	v_mfma_f32_16x16x32_bf16 v[84:87], v[160:163], v[124:127], v[84:87]
	v_mfma_f32_16x16x32_bf16 v[52:55], v[160:163], v[128:131], v[52:55]
	v_mfma_f32_16x16x32_bf16 v[20:23], v[160:163], v[132:135], v[20:23]
	s_waitcnt lgkmcnt(4)
	v_mfma_f32_16x16x32_bf16 v[112:115], v[164:167], v[120:123], v[112:115]
	v_mfma_f32_16x16x32_bf16 v[80:83], v[164:167], v[124:127], v[80:83]
	v_mfma_f32_16x16x32_bf16 v[48:51], v[164:167], v[128:131], v[48:51]
	v_mfma_f32_16x16x32_bf16 v[16:19], v[164:167], v[132:135], v[16:19]
	s_waitcnt lgkmcnt(3)
	v_mfma_f32_16x16x32_bf16 v[108:111], v[176:179], v[120:123], v[108:111]
	v_mfma_f32_16x16x32_bf16 v[76:79], v[176:179], v[124:127], v[76:79]
	v_mfma_f32_16x16x32_bf16 v[44:47], v[176:179], v[128:131], v[44:47]
	v_mfma_f32_16x16x32_bf16 v[12:15], v[176:179], v[132:135], v[12:15]
	s_waitcnt lgkmcnt(2)
	v_mfma_f32_16x16x32_bf16 v[104:107], v[180:183], v[120:123], v[104:107]
	v_mfma_f32_16x16x32_bf16 v[72:75], v[180:183], v[124:127], v[72:75]
	v_mfma_f32_16x16x32_bf16 v[40:43], v[180:183], v[128:131], v[40:43]
	v_mfma_f32_16x16x32_bf16 v[8:11], v[180:183], v[132:135], v[8:11]
	s_waitcnt lgkmcnt(0)
	s_waitcnt vmcnt(6)
	s_barrier
	ds_read_b128 v[136:139], v209 offset:49152
	ds_read_b128 v[140:143], v209 offset:50176
	ds_read_b128 v[144:147], v209 offset:51200
	ds_read_b128 v[148:151], v209 offset:52224
	ds_read_b128 v[152:155], v210 offset:57344
	ds_read_b128 v[156:159], v210 offset:58368
	ds_read_b128 v[160:163], v210 offset:59392
	ds_read_b128 v[164:167], v210 offset:60416
	ds_read_b128 v[176:179], v210 offset:61440
	ds_read_b128 v[180:183], v210 offset:62464
	v_mfma_f32_16x16x32_bf16 v[100:103], v[184:187], v[120:123], v[100:103]
	s_add_u32 m0, s11, 0x6000
	v_mfma_f32_16x16x32_bf16 v[68:71], v[184:187], v[124:127], v[68:71]
	global_load_lds_dwordx4 v203, s[2:3]
	s_add_u32 m0, s11, 0x6400
	v_mfma_f32_16x16x32_bf16 v[36:39], v[184:187], v[128:131], v[36:39]
	global_load_lds_dwordx4 v204, s[2:3]
	s_add_u32 m0, s12, 0x8000
	v_mfma_f32_16x16x32_bf16 v[4:7], v[184:187], v[132:135], v[4:7]
	global_load_lds_dwordx4 v205, s[4:5]
	s_add_u32 m0, s12, 0x8400
	v_mfma_f32_16x16x32_bf16 v[96:99], v[188:191], v[120:123], v[96:99]
	global_load_lds_dwordx4 v206, s[4:5]
	s_add_u32 m0, s12, 0x8800
	v_mfma_f32_16x16x32_bf16 v[64:67], v[188:191], v[124:127], v[64:67]
	global_load_lds_dwordx4 v207, s[4:5]
	s_add_u32 m0, s12, 0x8c00
	v_mfma_f32_16x16x32_bf16 v[32:35], v[188:191], v[128:131], v[32:35]
	global_load_lds_dwordx4 v208, s[4:5]
	v_mfma_f32_16x16x32_bf16 v[0:3], v[188:191], v[132:135], v[0:3]
	s_add_u32 s2, s2, 0x2000
	s_addc_u32 s3, s3, 0
	s_add_u32 s4, s4, 0x4000
	s_addc_u32 s5, s5, 0
	ds_read_b128 v[184:187], v210 offset:63488
	ds_read_b128 v[188:191], v210 offset:64512
	s_waitcnt lgkmcnt(7)
	v_mfma_f32_16x16x32_bf16 v[172:175], v[152:155], v[136:139], v[172:175]
	v_mfma_f32_16x16x32_bf16 v[92:95], v[152:155], v[140:143], v[92:95]
	v_mfma_f32_16x16x32_bf16 v[60:63], v[152:155], v[144:147], v[60:63]
	v_mfma_f32_16x16x32_bf16 v[28:31], v[152:155], v[148:151], v[28:31]
	s_waitcnt lgkmcnt(6)
	v_mfma_f32_16x16x32_bf16 v[168:171], v[156:159], v[136:139], v[168:171]
	v_mfma_f32_16x16x32_bf16 v[88:91], v[156:159], v[140:143], v[88:91]
	v_mfma_f32_16x16x32_bf16 v[56:59], v[156:159], v[144:147], v[56:59]
	v_mfma_f32_16x16x32_bf16 v[24:27], v[156:159], v[148:151], v[24:27]
	s_waitcnt lgkmcnt(5)
	v_mfma_f32_16x16x32_bf16 v[116:119], v[160:163], v[136:139], v[116:119]
	v_mfma_f32_16x16x32_bf16 v[84:87], v[160:163], v[140:143], v[84:87]
	v_mfma_f32_16x16x32_bf16 v[52:55], v[160:163], v[144:147], v[52:55]
	v_mfma_f32_16x16x32_bf16 v[20:23], v[160:163], v[148:151], v[20:23]
	s_waitcnt lgkmcnt(4)
	v_mfma_f32_16x16x32_bf16 v[112:115], v[164:167], v[136:139], v[112:115]
	v_mfma_f32_16x16x32_bf16 v[80:83], v[164:167], v[140:143], v[80:83]
	v_mfma_f32_16x16x32_bf16 v[48:51], v[164:167], v[144:147], v[48:51]
	v_mfma_f32_16x16x32_bf16 v[16:19], v[164:167], v[148:151], v[16:19]
	s_waitcnt lgkmcnt(3)
	v_mfma_f32_16x16x32_bf16 v[108:111], v[176:179], v[136:139], v[108:111]
	v_mfma_f32_16x16x32_bf16 v[76:79], v[176:179], v[140:143], v[76:79]
	v_mfma_f32_16x16x32_bf16 v[44:47], v[176:179], v[144:147], v[44:47]
	v_mfma_f32_16x16x32_bf16 v[12:15], v[176:179], v[148:151], v[12:15]
	s_waitcnt lgkmcnt(2)
	v_mfma_f32_16x16x32_bf16 v[104:107], v[180:183], v[136:139], v[104:107]
	v_mfma_f32_16x16x32_bf16 v[72:75], v[180:183], v[140:143], v[72:75]
	v_mfma_f32_16x16x32_bf16 v[40:43], v[180:183], v[144:147], v[40:43]
	v_mfma_f32_16x16x32_bf16 v[8:11], v[180:183], v[148:151], v[8:11]
	s_waitcnt lgkmcnt(0)
	s_waitcnt vmcnt(6)
	s_barrier
	ds_read_b128 v[120:123], v209 offset:0
	ds_read_b128 v[124:127], v209 offset:1024
	ds_read_b128 v[128:131], v209 offset:2048
	ds_read_b128 v[132:135], v209 offset:3072
	ds_read_b128 v[152:155], v210 offset:8192
	ds_read_b128 v[156:159], v210 offset:9216
	ds_read_b128 v[160:163], v210 offset:10240
	ds_read_b128 v[164:167], v210 offset:11264
	ds_read_b128 v[176:179], v210 offset:12288
	ds_read_b128 v[180:183], v210 offset:13312
	v_mfma_f32_16x16x32_bf16 v[100:103], v[184:187], v[136:139], v[100:103]
	s_add_u32 m0, s11, 0xc000
	v_mfma_f32_16x16x32_bf16 v[68:71], v[184:187], v[140:143], v[68:71]
	global_load_lds_dwordx4 v203, s[2:3]
	s_add_u32 m0, s11, 0xc400
	v_mfma_f32_16x16x32_bf16 v[36:39], v[184:187], v[144:147], v[36:39]
	global_load_lds_dwordx4 v204, s[2:3]
	s_add_u32 m0, s12, 0xe000
	v_mfma_f32_16x16x32_bf16 v[4:7], v[184:187], v[148:151], v[4:7]
	global_load_lds_dwordx4 v205, s[4:5]
	s_add_u32 m0, s12, 0xe400
	v_mfma_f32_16x16x32_bf16 v[96:99], v[188:191], v[136:139], v[96:99]
	global_load_lds_dwordx4 v206, s[4:5]
	s_add_u32 m0, s12, 0xe800
	v_mfma_f32_16x16x32_bf16 v[64:67], v[188:191], v[140:143], v[64:67]
	global_load_lds_dwordx4 v207, s[4:5]
	s_add_u32 m0, s12, 0xec00
	v_mfma_f32_16x16x32_bf16 v[32:35], v[188:191], v[144:147], v[32:35]
	global_load_lds_dwordx4 v208, s[4:5]
	v_mfma_f32_16x16x32_bf16 v[0:3], v[188:191], v[148:151], v[0:3]
	s_add_u32 s2, s2, 0x2000
	s_addc_u32 s3, s3, 0
	s_add_u32 s4, s4, 0x4000
	s_addc_u32 s5, s5, 0
	ds_read_b128 v[184:187], v210 offset:14336
	ds_read_b128 v[188:191], v210 offset:15360
	s_waitcnt lgkmcnt(7)
	v_mfma_f32_16x16x32_bf16 v[172:175], v[152:155], v[120:123], v[172:175]
	v_mfma_f32_16x16x32_bf16 v[92:95], v[152:155], v[124:127], v[92:95]
	v_mfma_f32_16x16x32_bf16 v[60:63], v[152:155], v[128:131], v[60:63]
	v_mfma_f32_16x16x32_bf16 v[28:31], v[152:155], v[132:135], v[28:31]
	s_waitcnt lgkmcnt(6)
	v_mfma_f32_16x16x32_bf16 v[168:171], v[156:159], v[120:123], v[168:171]
	v_mfma_f32_16x16x32_bf16 v[88:91], v[156:159], v[124:127], v[88:91]
	v_mfma_f32_16x16x32_bf16 v[56:59], v[156:159], v[128:131], v[56:59]
	v_mfma_f32_16x16x32_bf16 v[24:27], v[156:159], v[132:135], v[24:27]
	s_waitcnt lgkmcnt(5)
	v_mfma_f32_16x16x32_bf16 v[116:119], v[160:163], v[120:123], v[116:119]
	v_mfma_f32_16x16x32_bf16 v[84:87], v[160:163], v[124:127], v[84:87]
	v_mfma_f32_16x16x32_bf16 v[52:55], v[160:163], v[128:131], v[52:55]
	v_mfma_f32_16x16x32_bf16 v[20:23], v[160:163], v[132:135], v[20:23]
	s_waitcnt lgkmcnt(4)
	v_mfma_f32_16x16x32_bf16 v[112:115], v[164:167], v[120:123], v[112:115]
	v_mfma_f32_16x16x32_bf16 v[80:83], v[164:167], v[124:127], v[80:83]
	v_mfma_f32_16x16x32_bf16 v[48:51], v[164:167], v[128:131], v[48:51]
	v_mfma_f32_16x16x32_bf16 v[16:19], v[164:167], v[132:135], v[16:19]
	s_waitcnt lgkmcnt(3)
	v_mfma_f32_16x16x32_bf16 v[108:111], v[176:179], v[120:123], v[108:111]
	v_mfma_f32_16x16x32_bf16 v[76:79], v[176:179], v[124:127], v[76:79]
	v_mfma_f32_16x16x32_bf16 v[44:47], v[176:179], v[128:131], v[44:47]
	v_mfma_f32_16x16x32_bf16 v[12:15], v[176:179], v[132:135], v[12:15]
	s_waitcnt lgkmcnt(2)
	v_mfma_f32_16x16x32_bf16 v[104:107], v[180:183], v[120:123], v[104:107]
	v_mfma_f32_16x16x32_bf16 v[72:75], v[180:183], v[124:127], v[72:75]
	v_mfma_f32_16x16x32_bf16 v[40:43], v[180:183], v[128:131], v[40:43]
	v_mfma_f32_16x16x32_bf16 v[8:11], v[180:183], v[132:135], v[8:11]
	s_waitcnt lgkmcnt(0)
	s_sub_u32 s13, s13, 1
	s_cmp_lg_u32 s13, 0
	s_cbranch_scc1 .Lg1_loop
	s_waitcnt vmcnt(6)
	s_barrier
	ds_read_b128 v[136:139], v209 offset:24576
	ds_read_b128 v[140:143], v209 offset:25600
	ds_read_b128 v[144:147], v209 offset:26624
	ds_read_b128 v[148:151], v209 offset:27648
	ds_read_b128 v[152:155], v210 offset:32768
	ds_read_b128 v[156:159], v210 offset:33792
	ds_read_b128 v[160:163], v210 offset:34816
	ds_read_b128 v[164:167], v210 offset:35840
	ds_read_b128 v[176:179], v210 offset:36864
	ds_read_b128 v[180:183], v210 offset:37888
	v_mfma_f32_16x16x32_bf16 v[100:103], v[184:187], v[120:123], v[100:103]
	v_mfma_f32_16x16x32_bf16 v[68:71], v[184:187], v[124:127], v[68:71]
	v_mfma_f32_16x16x32_bf16 v[36:39], v[184:187], v[128:131], v[36:39]
	v_mfma_f32_16x16x32_bf16 v[4:7], v[184:187], v[132:135], v[4:7]
	v_mfma_f32_16x16x32_bf16 v[96:99], v[188:191], v[120:123], v[96:99]
	v_mfma_f32_16x16x32_bf16 v[64:67], v[188:191], v[124:127], v[64:67]
	v_mfma_f32_16x16x32_bf16 v[32:35], v[188:191], v[128:131], v[32:35]
	v_mfma_f32_16x16x32_bf16 v[0:3], v[188:191], v[132:135], v[0:3]
	ds_read_b128 v[184:187], v210 offset:38912
	ds_read_b128 v[188:191], v210 offset:39936
	s_waitcnt lgkmcnt(7)
	v_mfma_f32_16x16x32_bf16 v[172:175], v[152:155], v[136:139], v[172:175]
	v_mfma_f32_16x16x32_bf16 v[92:95], v[152:155], v[140:143], v[92:95]
	v_mfma_f32_16x16x32_bf16 v[60:63], v[152:155], v[144:147], v[60:63]
	v_mfma_f32_16x16x32_bf16 v[28:31], v[152:155], v[148:151], v[28:31]
	s_waitcnt lgkmcnt(6)
	v_mfma_f32_16x16x32_bf16 v[168:171], v[156:159], v[136:139], v[168:171]
	v_mfma_f32_16x16x32_bf16 v[88:91], v[156:159], v[140:143], v[88:91]
	v_mfma_f32_16x16x32_bf16 v[56:59], v[156:159], v[144:147], v[56:59]
	v_mfma_f32_16x16x32_bf16 v[24:27], v[156:159], v[148:151], v[24:27]
	s_waitcnt lgkmcnt(5)
	v_mfma_f32_16x16x32_bf16 v[116:119], v[160:163], v[136:139], v[116:119]
	v_mfma_f32_16x16x32_bf16 v[84:87], v[160:163], v[140:143], v[84:87]
	v_mfma_f32_16x16x32_bf16 v[52:55], v[160:163], v[144:147], v[52:55]
	v_mfma_f32_16x16x32_bf16 v[20:23], v[160:163], v[148:151], v[20:23]
	s_waitcnt lgkmcnt(4)
	v_mfma_f32_16x16x32_bf16 v[112:115], v[164:167], v[136:139], v[112:115]
	v_mfma_f32_16x16x32_bf16 v[80:83], v[164:167], v[140:143], v[80:83]
	v_mfma_f32_16x16x32_bf16 v[48:51], v[164:167], v[144:147], v[48:51]
	v_mfma_f32_16x16x32_bf16 v[16:19], v[164:167], v[148:151], v[16:19]
	s_waitcnt lgkmcnt(3)
	v_mfma_f32_16x16x32_bf16 v[108:111], v[176:179], v[136:139], v[108:111]
	v_mfma_f32_16x16x32_bf16 v[76:79], v[176:179], v[140:143], v[76:79]
	v_mfma_f32_16x16x32_bf16 v[44:47], v[176:179], v[144:147], v[44:47]
	v_mfma_f32_16x16x32_bf16 v[12:15], v[176:179], v[148:151], v[12:15]
	s_waitcnt lgkmcnt(2)
	v_mfma_f32_16x16x32_bf16 v[104:107], v[180:183], v[136:139], v[104:107]
	v_mfma_f32_16x16x32_bf16 v[72:75], v[180:183], v[140:143], v[72:75]
	v_mfma_f32_16x16x32_bf16 v[40:43], v[180:183], v[144:147], v[40:43]
	v_mfma_f32_16x16x32_bf16 v[8:11], v[180:183], v[148:151], v[8:11]
	s_waitcnt lgkmcnt(0)
	v_mfma_f32_16x16x32_bf16 v[100:103], v[184:187], v[136:139], v[100:103]
	v_mfma_f32_16x16x32_bf16 v[68:71], v[184:187], v[140:143], v[68:71]
	v_mfma_f32_16x16x32_bf16 v[36:39], v[184:187], v[144:147], v[36:39]
	v_mfma_f32_16x16x32_bf16 v[4:7], v[184:187], v[148:151], v[4:7]
	v_mfma_f32_16x16x32_bf16 v[96:99], v[188:191], v[136:139], v[96:99]
	v_mfma_f32_16x16x32_bf16 v[64:67], v[188:191], v[140:143], v[64:67]
	v_mfma_f32_16x16x32_bf16 v[32:35], v[188:191], v[144:147], v[32:35]
	v_mfma_f32_16x16x32_bf16 v[0:3], v[188:191], v[148:151], v[0:3]
	s_waitcnt vmcnt(0)
	s_nop 7
	s_nop 7
	s_branch .LBB0_89

.LBB0_839:
	v_ashrrev_i32_e32 v17, 31, v16
	v_lshlrev_b64 v[14:15], 12, v[16:17]
	v_lshl_add_u64 v[38:39], v[20:21], 0, v[14:15]
	s_waitcnt vmcnt(0)
	v_mov_b32_e32 v30, v100
	v_mov_b32_e32 v31, v101
	v_mov_b32_e32 v32, v102
	v_mov_b32_e32 v33, v103
	v_mov_b32_e32 v34, v104
	v_mov_b32_e32 v35, v105
	v_mov_b32_e32 v36, v106
	v_mov_b32_e32 v37, v107
	v_readlane_b32 s96, v253, 4
	v_readlane_b32 s97, v253, 5
	v_and_b32_e32 v15, 63, v216
	v_lshrrev_b32_e32 v14, 3, v15
	v_lshlrev_b32_e32 v14, 13, v14
	v_and_b32_e32 v15, 7, v15
	v_lshl_or_b32 v14, v15, 3, v14
	v_and_b32_e32 v15, 8, v16
	v_mul_u32_u24_e32 v15, 6, v15
	v_xor_b32_e32 v14, v14, v15
	v_and_b32_e32 v15, 0x7f, v16
	v_lshl_add_u32 v14, v15, 6, v14
	v_lshrrev_b32_e32 v15, 7, v16
	v_lshl_add_u32 v14, v15, 18, v14
	v_add_u32_e32 v16, s81, v16
	v_mov_b32_e32 v42, v30
	v_mov_b32_e32 v44, v31
	v_mov_b32_e32 v40, v30
	v_mov_b32_e32 v30, v31
	v_mov_b32_e32 v31, v35
	v_mov_b32_e32 v41, v34
	v_pk_mul_f32 v[30:31], v[30:31], v[30:31]
	v_mov_b32_e32 v43, v32
	v_pk_fma_f32 v[30:31], v[40:41], v[40:41], v[30:31]
	v_mov_b32_e32 v40, v32
	v_mov_b32_e32 v41, v36
	v_mov_b32_e32 v45, v33
	v_pk_fma_f32 v[30:31], v[40:41], v[40:41], v[30:31]
	v_mov_b32_e32 v32, v33
	v_mov_b32_e32 v33, v37
	v_pk_fma_f32 v[46:47], v[32:33], v[32:33], v[30:31]
	v_mov_b32_e32 v30, v108
	v_mov_b32_e32 v31, v109
	v_mov_b32_e32 v32, v110
	v_mov_b32_e32 v33, v111
	v_mov_b32_e32 v48, v34
	v_mov_b32_e32 v38, v112
	v_mov_b32_e32 v39, v113
	v_mov_b32_e32 v40, v114
	v_mov_b32_e32 v41, v115
	v_min_i32_e32 v116, s8, v16
	v_ashrrev_i32_e32 v117, 31, v116
	v_lshlrev_b64 v[116:117], 12, v[116:117]
	v_lshl_add_u64 v[116:117], v[20:21], 0, v[116:117]
	global_load_dwordx4 v[100:103], v[116:117], off
	global_load_dwordx4 v[104:107], v[116:117], off offset:1024
	global_load_dwordx4 v[108:111], v[116:117], off offset:2048
	global_load_dwordx4 v[112:115], v[116:117], off offset:3072
	v_mov_b32_e32 v49, v36
	v_mov_b32_e32 v36, v35
	v_add_f32_e32 v17, v46, v47
	v_mov_b32_e32 v34, v30
	v_mov_b32_e32 v50, v31
	v_mov_b32_e32 v52, v30
	v_mov_b32_e32 v30, v31
	v_mov_b32_e32 v31, v39
	v_mov_b32_e32 v53, v38
	v_pk_mul_f32 v[30:31], v[30:31], v[30:31]
	v_mov_b32_e32 v35, v32
	v_pk_fma_f32 v[30:31], v[52:53], v[52:53], v[30:31]
	v_mov_b32_e32 v52, v32
	v_mov_b32_e32 v53, v40
	v_mov_b32_e32 v51, v33
	v_pk_fma_f32 v[30:31], v[52:53], v[52:53], v[30:31]
	v_mov_b32_e32 v32, v33
	v_mov_b32_e32 v33, v41
	v_pk_fma_f32 v[30:31], v[32:33], v[32:33], v[30:31]
	s_nop 0
	v_add_f32_e32 v17, v17, v30
	v_add_f32_e32 v17, v17, v31
	ds_bpermute_b32 v30, v24, v17
	s_waitcnt lgkmcnt(0)
	v_add_f32_e32 v17, v17, v30
	ds_bpermute_b32 v30, v25, v17
	s_waitcnt lgkmcnt(0)
	v_add_f32_e32 v17, v17, v30
	ds_bpermute_b32 v30, v26, v17
	s_waitcnt lgkmcnt(0)
	v_add_f32_e32 v17, v17, v30
	ds_bpermute_b32 v30, v27, v17
	s_waitcnt lgkmcnt(0)
	v_add_f32_e32 v17, v17, v30
	ds_bpermute_b32 v30, v28, v17
	s_waitcnt lgkmcnt(0)
	v_add_f32_e32 v17, v17, v30
	ds_bpermute_b32 v30, v29, v17
	s_waitcnt lgkmcnt(0)
	v_add_f32_e32 v17, v17, v30
	v_fmamk_f32 v17, v17, 0x3a800000, v217
	v_cmp_gt_f32_e32 vcc, s75, v17
	v_mul_f32_e32 v30, 0x4b800000, v17
	s_nop 0
	v_cndmask_b32_e32 v17, v17, v30, vcc
	v_rsq_f32_e32 v17, v17
	s_nop 0
	v_mul_f32_e32 v30, 0x45800000, v17
	v_cndmask_b32_e32 v30, v17, v30, vcc
	v_pk_mul_f32 v[46:47], v[2:3], v[30:31] op_sel_hi:[1,0]
	v_pk_mul_f32 v[32:33], v[0:1], v[30:31] op_sel_hi:[1,0]
	v_pk_mul_f32 v[36:37], v[36:37], v[46:47]
	v_pk_mul_f32 v[46:47], v[8:9], v[30:31] op_sel_hi:[1,0]
	v_pk_mul_f32 v[32:33], v[42:43], v[32:33]
	v_pk_mul_f32 v[42:43], v[22:23], v[30:31] op_sel_hi:[1,0]
	v_pk_mul_f32 v[34:35], v[34:35], v[46:47]
	v_pk_mul_f32 v[46:47], v[6:7], v[30:31] op_sel_hi:[1,0]
	v_pk_mul_f32 v[42:43], v[44:45], v[42:43]
	v_pk_mul_f32 v[46:47], v[50:51], v[46:47]
	v_mov_b32_e32 v50, v38
	v_and_b32_sdwa v17, v33, v232 dst_sel:DWORD dst_unused:UNUSED_PAD src0_sel:WORD_1 src1_sel:DWORD
	v_and_b32_sdwa v38, v32, v232 dst_sel:DWORD dst_unused:UNUSED_PAD src0_sel:WORD_1 src1_sel:DWORD
	v_add3_u32 v32, v32, v38, s69
	v_add3_u32 v17, v33, v17, s69
	v_and_b32_sdwa v33, v43, v232 dst_sel:DWORD dst_unused:UNUSED_PAD src0_sel:WORD_1 src1_sel:DWORD
	v_and_b32_sdwa v38, v42, v232 dst_sel:DWORD dst_unused:UNUSED_PAD src0_sel:WORD_1 src1_sel:DWORD
	v_add3_u32 v33, v43, v33, s69
	v_add3_u32 v38, v42, v38, s69
	v_and_b32_e32 v33, 0xffff0000, v33
	v_and_b32_e32 v38, 0xffff0000, v38
	v_pk_mul_f32 v[44:45], v[4:5], v[30:31] op_sel_hi:[1,0]
	v_or_b32_sdwa v33, v33, v17 dst_sel:DWORD dst_unused:UNUSED_PAD src0_sel:DWORD src1_sel:WORD_1
	v_or_b32_sdwa v32, v38, v32 dst_sel:DWORD dst_unused:UNUSED_PAD src0_sel:DWORD src1_sel:WORD_1
	v_pk_mul_f32 v[44:45], v[48:49], v[44:45]
	global_store_dwordx2 v14, v[32:33], s[96:97]
	v_and_b32_sdwa v33, v37, v232 dst_sel:DWORD dst_unused:UNUSED_PAD src0_sel:WORD_1 src1_sel:DWORD
	v_and_b32_sdwa v38, v36, v232 dst_sel:DWORD dst_unused:UNUSED_PAD src0_sel:WORD_1 src1_sel:DWORD
	v_and_b32_sdwa v17, v45, v232 dst_sel:DWORD dst_unused:UNUSED_PAD src0_sel:WORD_1 src1_sel:DWORD
	v_and_b32_sdwa v32, v44, v232 dst_sel:DWORD dst_unused:UNUSED_PAD src0_sel:WORD_1 src1_sel:DWORD
	v_add3_u32 v33, v37, v33, s69
	v_add3_u32 v36, v36, v38, s69
	v_add3_u32 v32, v44, v32, s69
	v_add3_u32 v17, v45, v17, s69
	v_and_b32_e32 v33, 0xffff0000, v33
	v_and_b32_e32 v36, 0xffff0000, v36
	v_or_b32_sdwa v33, v33, v17 dst_sel:DWORD dst_unused:UNUSED_PAD src0_sel:DWORD src1_sel:WORD_1
	v_or_b32_sdwa v32, v36, v32 dst_sel:DWORD dst_unused:UNUSED_PAD src0_sel:DWORD src1_sel:WORD_1
	v_add_u32_e32 v14, 0x10000, v14
	global_store_dwordx2 v14, v[32:33], s[96:97]
	v_and_b32_sdwa v32, v34, v232 dst_sel:DWORD dst_unused:UNUSED_PAD src0_sel:WORD_1 src1_sel:DWORD
	v_add3_u32 v32, v34, v32, s69
	v_and_b32_sdwa v33, v47, v232 dst_sel:DWORD dst_unused:UNUSED_PAD src0_sel:WORD_1 src1_sel:DWORD
	v_and_b32_sdwa v34, v46, v232 dst_sel:DWORD dst_unused:UNUSED_PAD src0_sel:WORD_1 src1_sel:DWORD
	v_and_b32_sdwa v17, v35, v232 dst_sel:DWORD dst_unused:UNUSED_PAD src0_sel:WORD_1 src1_sel:DWORD
	v_add3_u32 v33, v47, v33, s69
	v_add3_u32 v34, v46, v34, s69
	v_pk_mul_f32 v[48:49], v[12:13], v[30:31] op_sel_hi:[1,0]
	v_mov_b32_e32 v51, v40
	v_pk_mul_f32 v[30:31], v[10:11], v[30:31] op_sel_hi:[1,0]
	v_mov_b32_e32 v40, v39
	v_add3_u32 v17, v35, v17, s69
	v_and_b32_e32 v33, 0xffff0000, v33
	v_and_b32_e32 v34, 0xffff0000, v34
	v_pk_mul_f32 v[30:31], v[40:41], v[30:31]
	v_or_b32_sdwa v33, v33, v17 dst_sel:DWORD dst_unused:UNUSED_PAD src0_sel:DWORD src1_sel:WORD_1
	v_or_b32_sdwa v32, v34, v32 dst_sel:DWORD dst_unused:UNUSED_PAD src0_sel:DWORD src1_sel:WORD_1
	v_pk_mul_f32 v[48:49], v[50:51], v[48:49]
	v_add_u32_e32 v14, 0x10000, v14
	global_store_dwordx2 v14, v[32:33], s[96:97]
	v_and_b32_sdwa v33, v31, v232 dst_sel:DWORD dst_unused:UNUSED_PAD src0_sel:WORD_1 src1_sel:DWORD
	v_and_b32_sdwa v34, v30, v232 dst_sel:DWORD dst_unused:UNUSED_PAD src0_sel:WORD_1 src1_sel:DWORD
	v_and_b32_sdwa v17, v49, v232 dst_sel:DWORD dst_unused:UNUSED_PAD src0_sel:WORD_1 src1_sel:DWORD
	v_and_b32_sdwa v32, v48, v232 dst_sel:DWORD dst_unused:UNUSED_PAD src0_sel:WORD_1 src1_sel:DWORD
	v_add3_u32 v31, v31, v33, s69
	v_add3_u32 v30, v30, v34, s69
	v_add3_u32 v32, v48, v32, s69
	v_add3_u32 v17, v49, v17, s69
	v_and_b32_e32 v31, 0xffff0000, v31
	v_and_b32_e32 v30, 0xffff0000, v30
	v_cmp_lt_i32_e32 vcc, s8, v16
	v_or_b32_sdwa v31, v31, v17 dst_sel:DWORD dst_unused:UNUSED_PAD src0_sel:DWORD src1_sel:WORD_1
	v_or_b32_sdwa v30, v30, v32 dst_sel:DWORD dst_unused:UNUSED_PAD src0_sel:DWORD src1_sel:WORD_1
	s_or_b64 s[4:5], vcc, s[4:5]
	v_add_u32_e32 v14, 0x10000, v14
	global_store_dwordx2 v14, v[30:31], s[96:97]
	s_andn2_b64 exec, exec, s[4:5]
	s_cbranch_execnz .LBB0_839

.LBB0_896:
	s_andn2_b64 vcc, exec, s[2:3]
	s_cbranch_vccnz .LBB0_890
	v_readlane_b32 s11, v254, 62
	v_readlane_b32 s12, v254, 60
	v_readlane_b32 s2, v253, 4
	v_readlane_b32 s3, v253, 5
	s_lshl_b32 s13, s11, 18
	s_add_u32 s2, s2, s13
	s_addc_u32 s3, s3, 0
	s_lshl_b32 s13, s12, 19
	s_add_u32 s4, s50, 0x65d0000
	s_addc_u32 s5, s51, 0
	s_add_u32 s4, s4, s13
	s_addc_u32 s5, s5, 0
	v_and_b32_e32 v152, 63, v216
	v_lshrrev_b32_e32 v153, 6, v216
	v_lshrrev_b32_e32 v154, 2, v152
	v_and_b32_e32 v155, 3, v152
	v_readfirstlane_b32 s11, v153
	v_lshrrev_b32_e32 v156, 3, v154
	v_mul_u32_u24_e32 v156, 3, v156
	v_xor_b32_e32 v156, v155, v156
	v_lshlrev_b32_e32 v156, 4, v156
	v_lshl_add_u32 v157, v153, 5, v154
	v_lshlrev_b32_e32 v163, 4, v152
	v_lshl_add_u32 v203, v153, 11, v163
	v_add_u32_e32 v204, 0x400, v203
	v_lshl_add_u32 v157, v153, 6, v154
	v_lshlrev_b32_e32 v163, 4, v152
	v_lshl_add_u32 v205, v153, 12, v163
	v_add_u32_e32 v206, 0x400, v205
	v_add_u32_e32 v207, 0x800, v205
	v_add_u32_e32 v208, 0xc00, v205
	v_and_b32_e32 v158, 15, v152
	v_lshrrev_b32_e32 v159, 4, v152
	v_lshrrev_b32_e32 v160, 3, v158
	v_mul_u32_u24_e32 v160, 3, v160
	v_xor_b32_e32 v160, v159, v160
	v_lshlrev_b32_e32 v160, 4, v160
	v_lshl_add_u32 v160, v158, 6, v160
	v_lshrrev_b32_e32 v161, 1, v153
	v_and_b32_e32 v162, 1, v153
	v_lshl_add_u32 v209, v161, 12, v160
	v_lshl_add_u32 v210, v162, 13, v160
	s_lshl_b32 s12, s11, 12
	s_lshl_b32 s11, s11, 11
	s_barrier
	s_add_u32 m0, s11, 0x0
	s_nop 0
	global_load_lds_dwordx4 v203, s[2:3]
	s_add_u32 m0, s11, 0x400
	s_nop 0
	global_load_lds_dwordx4 v204, s[2:3]
	s_add_u32 m0, s12, 0x2000
	s_nop 0
	global_load_lds_dwordx4 v205, s[4:5]
	s_add_u32 m0, s12, 0x2400
	s_nop 0
	global_load_lds_dwordx4 v206, s[4:5]
	s_add_u32 m0, s12, 0x2800
	s_nop 0
	global_load_lds_dwordx4 v207, s[4:5]
	s_add_u32 m0, s12, 0x2c00
	s_nop 0
	global_load_lds_dwordx4 v208, s[4:5]
	s_add_u32 s2, s2, 0x2000
	s_addc_u32 s3, s3, 0
	s_add_u32 s4, s4, 0x4000
	s_addc_u32 s5, s5, 0
	s_add_u32 m0, s11, 0x6000
	s_nop 0
	global_load_lds_dwordx4 v203, s[2:3]
	s_add_u32 m0, s11, 0x6400
	s_nop 0
	global_load_lds_dwordx4 v204, s[2:3]
	s_add_u32 m0, s12, 0x8000
	s_nop 0
	global_load_lds_dwordx4 v205, s[4:5]
	s_add_u32 m0, s12, 0x8400
	s_nop 0
	global_load_lds_dwordx4 v206, s[4:5]
	s_add_u32 m0, s12, 0x8800
	s_nop 0
	global_load_lds_dwordx4 v207, s[4:5]
	s_add_u32 m0, s12, 0x8c00
	s_nop 0
	global_load_lds_dwordx4 v208, s[4:5]
	s_add_u32 s2, s2, 0x2000
	s_addc_u32 s3, s3, 0
	s_add_u32 s4, s4, 0x4000
	s_addc_u32 s5, s5, 0
	v_mov_b32_e32 v172, 0
	v_mov_b32_e32 v173, 0
	v_mov_b32_e32 v174, 0
	v_mov_b32_e32 v175, 0
	v_mov_b32_e32 v168, 0
	v_mov_b32_e32 v169, 0
	v_mov_b32_e32 v170, 0
	v_mov_b32_e32 v171, 0
	v_mov_b32_e32 v116, 0
	v_mov_b32_e32 v117, 0
	v_mov_b32_e32 v118, 0
	v_mov_b32_e32 v119, 0
	v_mov_b32_e32 v112, 0
	v_mov_b32_e32 v113, 0
	v_mov_b32_e32 v114, 0
	v_mov_b32_e32 v115, 0
	v_mov_b32_e32 v108, 0
	v_mov_b32_e32 v109, 0
	v_mov_b32_e32 v110, 0
	v_mov_b32_e32 v111, 0
	v_mov_b32_e32 v104, 0
	v_mov_b32_e32 v105, 0
	v_mov_b32_e32 v106, 0
	v_mov_b32_e32 v107, 0
	v_mov_b32_e32 v100, 0
	v_mov_b32_e32 v101, 0
	v_mov_b32_e32 v102, 0
	v_mov_b32_e32 v103, 0
	v_mov_b32_e32 v96, 0
	v_mov_b32_e32 v97, 0
	v_mov_b32_e32 v98, 0
	v_mov_b32_e32 v99, 0
	v_mov_b32_e32 v92, 0
	v_mov_b32_e32 v93, 0
	v_mov_b32_e32 v94, 0
	v_mov_b32_e32 v95, 0
	v_mov_b32_e32 v88, 0
	v_mov_b32_e32 v89, 0
	v_mov_b32_e32 v90, 0
	v_mov_b32_e32 v91, 0
	v_mov_b32_e32 v84, 0
	v_mov_b32_e32 v85, 0
	v_mov_b32_e32 v86, 0
	v_mov_b32_e32 v87, 0
	v_mov_b32_e32 v80, 0
	v_mov_b32_e32 v81, 0
	v_mov_b32_e32 v82, 0
	v_mov_b32_e32 v83, 0
	v_mov_b32_e32 v76, 0
	v_mov_b32_e32 v77, 0
	v_mov_b32_e32 v78, 0
	v_mov_b32_e32 v79, 0
	v_mov_b32_e32 v72, 0
	v_mov_b32_e32 v73, 0
	v_mov_b32_e32 v74, 0
	v_mov_b32_e32 v75, 0
	v_mov_b32_e32 v68, 0
	v_mov_b32_e32 v69, 0
	v_mov_b32_e32 v70, 0
	v_mov_b32_e32 v71, 0
	v_mov_b32_e32 v64, 0
	v_mov_b32_e32 v65, 0
	v_mov_b32_e32 v66, 0
	v_mov_b32_e32 v67, 0
	v_mov_b32_e32 v60, 0
	v_mov_b32_e32 v61, 0
	v_mov_b32_e32 v62, 0
	v_mov_b32_e32 v63, 0
	v_mov_b32_e32 v56, 0
	v_mov_b32_e32 v57, 0
	v_mov_b32_e32 v58, 0
	v_mov_b32_e32 v59, 0
	v_mov_b32_e32 v52, 0
	v_mov_b32_e32 v53, 0
	v_mov_b32_e32 v54, 0
	v_mov_b32_e32 v55, 0
	v_mov_b32_e32 v48, 0
	v_mov_b32_e32 v49, 0
	v_mov_b32_e32 v50, 0
	v_mov_b32_e32 v51, 0
	v_mov_b32_e32 v44, 0
	v_mov_b32_e32 v45, 0
	v_mov_b32_e32 v46, 0
	v_mov_b32_e32 v47, 0
	v_mov_b32_e32 v40, 0
	v_mov_b32_e32 v41, 0
	v_mov_b32_e32 v42, 0
	v_mov_b32_e32 v43, 0
	v_mov_b32_e32 v36, 0
	v_mov_b32_e32 v37, 0
	v_mov_b32_e32 v38, 0
	v_mov_b32_e32 v39, 0
	v_mov_b32_e32 v32, 0
	v_mov_b32_e32 v33, 0
	v_mov_b32_e32 v34, 0
	v_mov_b32_e32 v35, 0
	v_mov_b32_e32 v28, 0
	v_mov_b32_e32 v29, 0
	v_mov_b32_e32 v30, 0
	v_mov_b32_e32 v31, 0
	v_mov_b32_e32 v24, 0
	v_mov_b32_e32 v25, 0
	v_mov_b32_e32 v26, 0
	v_mov_b32_e32 v27, 0
	v_mov_b32_e32 v20, 0
	v_mov_b32_e32 v21, 0
	v_mov_b32_e32 v22, 0
	v_mov_b32_e32 v23, 0
	v_mov_b32_e32 v16, 0
	v_mov_b32_e32 v17, 0
	v_mov_b32_e32 v18, 0
	v_mov_b32_e32 v19, 0
	v_mov_b32_e32 v12, 0
	v_mov_b32_e32 v13, 0
	v_mov_b32_e32 v14, 0
	v_mov_b32_e32 v15, 0
	v_mov_b32_e32 v8, 0
	v_mov_b32_e32 v9, 0
	v_mov_b32_e32 v10, 0
	v_mov_b32_e32 v11, 0
	v_mov_b32_e32 v4, 0
	v_mov_b32_e32 v5, 0
	v_mov_b32_e32 v6, 0
	v_mov_b32_e32 v7, 0
	v_mov_b32_e32 v0, 0
	v_mov_b32_e32 v1, 0
	v_mov_b32_e32 v2, 0
	v_mov_b32_e32 v3, 0
	s_waitcnt vmcnt(6)
	s_barrier
	ds_read_b128 v[120:123], v209 offset:0
	ds_read_b128 v[124:127], v209 offset:1024
	ds_read_b128 v[128:131], v209 offset:2048
	ds_read_b128 v[132:135], v209 offset:3072
	ds_read_b128 v[152:155], v210 offset:8192
	ds_read_b128 v[156:159], v210 offset:9216
	ds_read_b128 v[160:163], v210 offset:10240
	ds_read_b128 v[164:167], v210 offset:11264
	ds_read_b128 v[176:179], v210 offset:12288
	ds_read_b128 v[180:183], v210 offset:13312
	s_add_u32 m0, s11, 0xc000
	s_nop 0
	global_load_lds_dwordx4 v203, s[2:3]
	s_add_u32 m0, s11, 0xc400
	s_nop 0
	global_load_lds_dwordx4 v204, s[2:3]
	s_add_u32 m0, s12, 0xe000
	s_nop 0
	global_load_lds_dwordx4 v205, s[4:5]
	s_add_u32 m0, s12, 0xe400
	s_nop 0
	global_load_lds_dwordx4 v206, s[4:5]
	s_add_u32 m0, s12, 0xe800
	s_nop 0
	global_load_lds_dwordx4 v207, s[4:5]
	s_add_u32 m0, s12, 0xec00
	s_nop 0
	global_load_lds_dwordx4 v208, s[4:5]
	s_add_u32 s2, s2, 0x2000
	s_addc_u32 s3, s3, 0
	s_add_u32 s4, s4, 0x4000
	s_addc_u32 s5, s5, 0
	ds_read_b128 v[184:187], v210 offset:14336
	ds_read_b128 v[188:191], v210 offset:15360
	s_waitcnt lgkmcnt(7)
	v_mfma_f32_16x16x32_bf16 v[172:175], v[152:155], v[120:123], v[172:175]
	v_mfma_f32_16x16x32_bf16 v[92:95], v[152:155], v[124:127], v[92:95]
	v_mfma_f32_16x16x32_bf16 v[60:63], v[152:155], v[128:131], v[60:63]
	v_mfma_f32_16x16x32_bf16 v[28:31], v[152:155], v[132:135], v[28:31]
	s_waitcnt lgkmcnt(6)
	v_mfma_f32_16x16x32_bf16 v[168:171], v[156:159], v[120:123], v[168:171]
	v_mfma_f32_16x16x32_bf16 v[88:91], v[156:159], v[124:127], v[88:91]
	v_mfma_f32_16x16x32_bf16 v[56:59], v[156:159], v[128:131], v[56:59]
	v_mfma_f32_16x16x32_bf16 v[24:27], v[156:159], v[132:135], v[24:27]
	s_waitcnt lgkmcnt(5)
	v_mfma_f32_16x16x32_bf16 v[116:119], v[160:163], v[120:123], v[116:119]
	v_mfma_f32_16x16x32_bf16 v[84:87], v[160:163], v[124:127], v[84:87]
	v_mfma_f32_16x16x32_bf16 v[52:55], v[160:163], v[128:131], v[52:55]
	v_mfma_f32_16x16x32_bf16 v[20:23], v[160:163], v[132:135], v[20:23]
	s_waitcnt lgkmcnt(4)
	v_mfma_f32_16x16x32_bf16 v[112:115], v[164:167], v[120:123], v[112:115]
	v_mfma_f32_16x16x32_bf16 v[80:83], v[164:167], v[124:127], v[80:83]
	v_mfma_f32_16x16x32_bf16 v[48:51], v[164:167], v[128:131], v[48:51]
	v_mfma_f32_16x16x32_bf16 v[16:19], v[164:167], v[132:135], v[16:19]
	s_waitcnt lgkmcnt(3)
	v_mfma_f32_16x16x32_bf16 v[108:111], v[176:179], v[120:123], v[108:111]
	v_mfma_f32_16x16x32_bf16 v[76:79], v[176:179], v[124:127], v[76:79]
	v_mfma_f32_16x16x32_bf16 v[44:47], v[176:179], v[128:131], v[44:47]
	v_mfma_f32_16x16x32_bf16 v[12:15], v[176:179], v[132:135], v[12:15]
	s_waitcnt lgkmcnt(2)
	v_mfma_f32_16x16x32_bf16 v[104:107], v[180:183], v[120:123], v[104:107]
	v_mfma_f32_16x16x32_bf16 v[72:75], v[180:183], v[124:127], v[72:75]
	v_mfma_f32_16x16x32_bf16 v[40:43], v[180:183], v[128:131], v[40:43]
	v_mfma_f32_16x16x32_bf16 v[8:11], v[180:183], v[132:135], v[8:11]
	s_waitcnt lgkmcnt(0)
	s_mov_b32 s13, 5
